# v6 + P6 sample-row split-K GEMM K-sequence re-pipelined to a 3-stage register ring (two 12-load steps in flight), MFMA chain order unchanged
# baseline (speedup 1.0000x reference)
.LBB0_1030:
	s_and_b32 s11, s19, 0x3e0
	v_or_b32_e32 v93, s11, v88
	v_or_b32_e32 v94, 0x8000, v93
	s_add_i32 s10, s68, s3
	v_mul_u32_u24_e32 v0, 0xb00, v94
	s_ashr_i32 s10, s10, 5
	v_lshlrev_b32_e32 v84, 1, v0
	s_lshl_b32 s11, s10, 6
	v_lshl_add_u64 v[0:1], v[80:81], 0, v[84:85]
	v_or_b32_e32 v4, s11, v88
	v_add_co_u32_e32 v2, vcc, 0x16000, v0
	v_mad_i64_i32 v[4:5], s[16:17], v4, s33, v[82:83]
	s_nop 0
	v_addc_co_u32_e32 v3, vcc, 0, v1, vcc
	v_add_co_u32_e32 v6, vcc, 0x16000, v4
	v_addc_co_u32_e32 v7, vcc, 0, v5, vcc
	v_add_co_u32_e32 v8, vcc, 0x2c000, v4
	v_addc_co_u32_e32 v9, vcc, 0, v5, vcc
	v_add_co_u32_e32 v10, vcc, 0x42000, v4
	v_addc_co_u32_e32 v11, vcc, 0, v5, vcc
	global_load_dwordx4 v[48:51], v[0:1], off
	global_load_dwordx4 v[52:55], v[0:1], off offset:64
	global_load_dwordx4 v[56:59], v[2:3], off
	global_load_dwordx4 v[60:63], v[2:3], off offset:64
	global_load_dwordx4 v[96:99], v[4:5], off
	global_load_dwordx4 v[100:103], v[4:5], off offset:64
	global_load_dwordx4 v[104:107], v[6:7], off
	global_load_dwordx4 v[108:111], v[6:7], off offset:64
	global_load_dwordx4 v[112:115], v[8:9], off
	global_load_dwordx4 v[116:119], v[8:9], off offset:64
	global_load_dwordx4 v[120:123], v[10:11], off
	global_load_dwordx4 v[124:127], v[10:11], off offset:64
	global_load_dwordx4 v[128:131], v[0:1], off offset:128
	global_load_dwordx4 v[132:135], v[0:1], off offset:192
	global_load_dwordx4 v[136:139], v[2:3], off offset:128
	global_load_dwordx4 v[140:143], v[2:3], off offset:192
	global_load_dwordx4 v[144:147], v[4:5], off offset:128
	global_load_dwordx4 v[148:151], v[4:5], off offset:192
	global_load_dwordx4 v[152:155], v[6:7], off offset:128
	global_load_dwordx4 v[156:159], v[6:7], off offset:192
	global_load_dwordx4 v[160:163], v[8:9], off offset:128
	global_load_dwordx4 v[164:167], v[8:9], off offset:192
	global_load_dwordx4 v[168:171], v[10:11], off offset:128
	global_load_dwordx4 v[172:175], v[10:11], off offset:192
	global_load_dwordx4 v[176:179], v[0:1], off offset:256
	global_load_dwordx4 v[180:183], v[0:1], off offset:320
	global_load_dwordx4 v[188:191], v[2:3], off offset:256
	global_load_dwordx4 v[192:195], v[2:3], off offset:320
	global_load_dwordx4 v[196:199], v[4:5], off offset:256
	global_load_dwordx4 v[200:203], v[4:5], off offset:320
	global_load_dwordx4 v[204:207], v[6:7], off offset:256
	global_load_dwordx4 v[208:211], v[6:7], off offset:320
	global_load_dwordx4 v[212:215], v[8:9], off offset:256
	global_load_dwordx4 v[224:227], v[8:9], off offset:320
	global_load_dwordx4 v[228:231], v[10:11], off offset:256
	global_load_dwordx4 v[232:235], v[10:11], off offset:320
	s_waitcnt vmcnt(31)
	v_mfma_f32_16x16x32_bf16 v[16:19], v[96:99], v[48:51], 0
	s_waitcnt vmcnt(29)
	v_mfma_f32_16x16x32_bf16 v[20:23], v[104:107], v[48:51], 0
	s_waitcnt vmcnt(27)
	v_mfma_f32_16x16x32_bf16 v[24:27], v[112:115], v[48:51], 0
	s_waitcnt vmcnt(25)
	v_mfma_f32_16x16x32_bf16 v[28:31], v[120:123], v[48:51], 0
	v_mfma_f32_16x16x32_bf16 v[16:19], v[100:103], v[52:55], v[16:19]
	v_mfma_f32_16x16x32_bf16 v[20:23], v[108:111], v[52:55], v[20:23]
	v_mfma_f32_16x16x32_bf16 v[24:27], v[116:119], v[52:55], v[24:27]
	s_waitcnt vmcnt(24)
	v_mfma_f32_16x16x32_bf16 v[28:31], v[124:127], v[52:55], v[28:31]
	v_mfma_f32_16x16x32_bf16 v[32:35], v[96:99], v[56:59], 0
	v_mfma_f32_16x16x32_bf16 v[32:35], v[100:103], v[60:63], v[32:35]
	v_mfma_f32_16x16x32_bf16 v[36:39], v[104:107], v[56:59], 0
	v_mfma_f32_16x16x32_bf16 v[40:43], v[112:115], v[56:59], 0
	v_mfma_f32_16x16x32_bf16 v[44:47], v[120:123], v[56:59], 0
	v_mfma_f32_16x16x32_bf16 v[36:39], v[108:111], v[60:63], v[36:39]
	v_mfma_f32_16x16x32_bf16 v[40:43], v[116:119], v[60:63], v[40:43]
	v_mfma_f32_16x16x32_bf16 v[44:47], v[124:127], v[60:63], v[44:47]
	global_load_dwordx4 v[48:51], v[0:1], off offset:384
	global_load_dwordx4 v[52:55], v[0:1], off offset:448
	global_load_dwordx4 v[56:59], v[2:3], off offset:384
	global_load_dwordx4 v[60:63], v[2:3], off offset:448
	global_load_dwordx4 v[96:99], v[4:5], off offset:384
	global_load_dwordx4 v[100:103], v[4:5], off offset:448
	global_load_dwordx4 v[104:107], v[6:7], off offset:384
	global_load_dwordx4 v[108:111], v[6:7], off offset:448
	global_load_dwordx4 v[112:115], v[8:9], off offset:384
	global_load_dwordx4 v[116:119], v[8:9], off offset:448
	global_load_dwordx4 v[120:123], v[10:11], off offset:384
	global_load_dwordx4 v[124:127], v[10:11], off offset:448
	s_waitcnt vmcnt(25)
	v_mfma_f32_16x16x32_bf16 v[28:31], v[168:171], v[128:131], v[28:31]
	v_mfma_f32_16x16x32_bf16 v[16:19], v[144:147], v[128:131], v[16:19]
	v_mfma_f32_16x16x32_bf16 v[20:23], v[152:155], v[128:131], v[20:23]
	v_mfma_f32_16x16x32_bf16 v[24:27], v[160:163], v[128:131], v[24:27]
	s_waitcnt vmcnt(24)
	v_mfma_f32_16x16x32_bf16 v[28:31], v[172:175], v[132:135], v[28:31]
	v_mfma_f32_16x16x32_bf16 v[32:35], v[144:147], v[136:139], v[32:35]
	v_mfma_f32_16x16x32_bf16 v[36:39], v[152:155], v[136:139], v[36:39]
	v_mfma_f32_16x16x32_bf16 v[40:43], v[160:163], v[136:139], v[40:43]
	v_mfma_f32_16x16x32_bf16 v[44:47], v[168:171], v[136:139], v[44:47]
	v_mfma_f32_16x16x32_bf16 v[16:19], v[148:151], v[132:135], v[16:19]
	v_mfma_f32_16x16x32_bf16 v[20:23], v[156:159], v[132:135], v[20:23]
	v_mfma_f32_16x16x32_bf16 v[24:27], v[164:167], v[132:135], v[24:27]
	v_mfma_f32_16x16x32_bf16 v[32:35], v[148:151], v[140:143], v[32:35]
	v_mfma_f32_16x16x32_bf16 v[36:39], v[156:159], v[140:143], v[36:39]
	v_mfma_f32_16x16x32_bf16 v[40:43], v[164:167], v[140:143], v[40:43]
	v_mfma_f32_16x16x32_bf16 v[44:47], v[172:175], v[140:143], v[44:47]
	global_load_dwordx4 v[128:131], v[0:1], off offset:512
	global_load_dwordx4 v[132:135], v[0:1], off offset:576
	global_load_dwordx4 v[136:139], v[2:3], off offset:512
	global_load_dwordx4 v[140:143], v[2:3], off offset:576
	global_load_dwordx4 v[144:147], v[4:5], off offset:512
	global_load_dwordx4 v[148:151], v[4:5], off offset:576
	global_load_dwordx4 v[152:155], v[6:7], off offset:512
	global_load_dwordx4 v[156:159], v[6:7], off offset:576
	global_load_dwordx4 v[160:163], v[8:9], off offset:512
	global_load_dwordx4 v[164:167], v[8:9], off offset:576
	global_load_dwordx4 v[168:171], v[10:11], off offset:512
	global_load_dwordx4 v[172:175], v[10:11], off offset:576
	s_waitcnt vmcnt(25)
	v_mfma_f32_16x16x32_bf16 v[28:31], v[228:231], v[176:179], v[28:31]
	v_mfma_f32_16x16x32_bf16 v[16:19], v[196:199], v[176:179], v[16:19]
	v_mfma_f32_16x16x32_bf16 v[20:23], v[204:207], v[176:179], v[20:23]
	v_mfma_f32_16x16x32_bf16 v[24:27], v[212:215], v[176:179], v[24:27]
	s_waitcnt vmcnt(24)
	v_mfma_f32_16x16x32_bf16 v[28:31], v[232:235], v[180:183], v[28:31]
	v_mfma_f32_16x16x32_bf16 v[32:35], v[196:199], v[188:191], v[32:35]
	v_mfma_f32_16x16x32_bf16 v[36:39], v[204:207], v[188:191], v[36:39]
	v_mfma_f32_16x16x32_bf16 v[40:43], v[212:215], v[188:191], v[40:43]
	v_mfma_f32_16x16x32_bf16 v[44:47], v[228:231], v[188:191], v[44:47]
	v_mfma_f32_16x16x32_bf16 v[16:19], v[200:203], v[180:183], v[16:19]
	v_mfma_f32_16x16x32_bf16 v[20:23], v[208:211], v[180:183], v[20:23]
	v_mfma_f32_16x16x32_bf16 v[24:27], v[224:227], v[180:183], v[24:27]
	v_mfma_f32_16x16x32_bf16 v[32:35], v[200:203], v[192:195], v[32:35]
	v_mfma_f32_16x16x32_bf16 v[36:39], v[208:211], v[192:195], v[36:39]
	v_mfma_f32_16x16x32_bf16 v[40:43], v[224:227], v[192:195], v[40:43]
	v_mfma_f32_16x16x32_bf16 v[44:47], v[232:235], v[192:195], v[44:47]
	global_load_dwordx4 v[176:179], v[0:1], off offset:640
	global_load_dwordx4 v[180:183], v[0:1], off offset:704
	global_load_dwordx4 v[188:191], v[2:3], off offset:640
	global_load_dwordx4 v[192:195], v[2:3], off offset:704
	global_load_dwordx4 v[196:199], v[4:5], off offset:640
	global_load_dwordx4 v[200:203], v[4:5], off offset:704
	global_load_dwordx4 v[204:207], v[6:7], off offset:640
	global_load_dwordx4 v[208:211], v[6:7], off offset:704
	global_load_dwordx4 v[212:215], v[8:9], off offset:640
	global_load_dwordx4 v[224:227], v[8:9], off offset:704
	global_load_dwordx4 v[228:231], v[10:11], off offset:640
	global_load_dwordx4 v[232:235], v[10:11], off offset:704
	s_waitcnt vmcnt(25)
	v_mfma_f32_16x16x32_bf16 v[28:31], v[120:123], v[48:51], v[28:31]
	v_mfma_f32_16x16x32_bf16 v[16:19], v[96:99], v[48:51], v[16:19]
	v_mfma_f32_16x16x32_bf16 v[20:23], v[104:107], v[48:51], v[20:23]
	v_mfma_f32_16x16x32_bf16 v[24:27], v[112:115], v[48:51], v[24:27]
	s_waitcnt vmcnt(24)
	v_mfma_f32_16x16x32_bf16 v[28:31], v[124:127], v[52:55], v[28:31]
	v_mfma_f32_16x16x32_bf16 v[32:35], v[96:99], v[56:59], v[32:35]
	v_mfma_f32_16x16x32_bf16 v[36:39], v[104:107], v[56:59], v[36:39]
	v_mfma_f32_16x16x32_bf16 v[40:43], v[112:115], v[56:59], v[40:43]
	v_mfma_f32_16x16x32_bf16 v[44:47], v[120:123], v[56:59], v[44:47]
	v_mfma_f32_16x16x32_bf16 v[16:19], v[100:103], v[52:55], v[16:19]
	v_mfma_f32_16x16x32_bf16 v[20:23], v[108:111], v[52:55], v[20:23]
	v_mfma_f32_16x16x32_bf16 v[24:27], v[116:119], v[52:55], v[24:27]
	v_mfma_f32_16x16x32_bf16 v[32:35], v[100:103], v[60:63], v[32:35]
	v_mfma_f32_16x16x32_bf16 v[36:39], v[108:111], v[60:63], v[36:39]
	v_mfma_f32_16x16x32_bf16 v[40:43], v[116:119], v[60:63], v[40:43]
	v_mfma_f32_16x16x32_bf16 v[44:47], v[124:127], v[60:63], v[44:47]
	global_load_dwordx4 v[48:51], v[0:1], off offset:768
	global_load_dwordx4 v[52:55], v[0:1], off offset:832
	global_load_dwordx4 v[56:59], v[2:3], off offset:768
	global_load_dwordx4 v[60:63], v[2:3], off offset:832
	global_load_dwordx4 v[96:99], v[4:5], off offset:768
	global_load_dwordx4 v[100:103], v[4:5], off offset:832
	global_load_dwordx4 v[104:107], v[6:7], off offset:768
	global_load_dwordx4 v[108:111], v[6:7], off offset:832
	global_load_dwordx4 v[112:115], v[8:9], off offset:768
	global_load_dwordx4 v[116:119], v[8:9], off offset:832
	global_load_dwordx4 v[120:123], v[10:11], off offset:768
	global_load_dwordx4 v[124:127], v[10:11], off offset:832
	s_waitcnt vmcnt(25)
	v_mfma_f32_16x16x32_bf16 v[28:31], v[168:171], v[128:131], v[28:31]
	v_mfma_f32_16x16x32_bf16 v[16:19], v[144:147], v[128:131], v[16:19]
	v_mfma_f32_16x16x32_bf16 v[20:23], v[152:155], v[128:131], v[20:23]
	v_mfma_f32_16x16x32_bf16 v[24:27], v[160:163], v[128:131], v[24:27]
	s_waitcnt vmcnt(24)
	v_mfma_f32_16x16x32_bf16 v[28:31], v[172:175], v[132:135], v[28:31]
	v_mfma_f32_16x16x32_bf16 v[32:35], v[144:147], v[136:139], v[32:35]
	v_mfma_f32_16x16x32_bf16 v[36:39], v[152:155], v[136:139], v[36:39]
	v_mfma_f32_16x16x32_bf16 v[40:43], v[160:163], v[136:139], v[40:43]
	v_mfma_f32_16x16x32_bf16 v[44:47], v[168:171], v[136:139], v[44:47]
	v_mfma_f32_16x16x32_bf16 v[16:19], v[148:151], v[132:135], v[16:19]
	v_mfma_f32_16x16x32_bf16 v[20:23], v[156:159], v[132:135], v[20:23]
	v_mfma_f32_16x16x32_bf16 v[24:27], v[164:167], v[132:135], v[24:27]
	v_mfma_f32_16x16x32_bf16 v[32:35], v[148:151], v[140:143], v[32:35]
	v_mfma_f32_16x16x32_bf16 v[36:39], v[156:159], v[140:143], v[36:39]
	v_mfma_f32_16x16x32_bf16 v[40:43], v[164:167], v[140:143], v[40:43]
	v_mfma_f32_16x16x32_bf16 v[44:47], v[172:175], v[140:143], v[44:47]
	global_load_dwordx4 v[128:131], v[0:1], off offset:896
	global_load_dwordx4 v[132:135], v[0:1], off offset:960
	global_load_dwordx4 v[136:139], v[2:3], off offset:896
	global_load_dwordx4 v[140:143], v[2:3], off offset:960
	global_load_dwordx4 v[144:147], v[4:5], off offset:896
	global_load_dwordx4 v[148:151], v[4:5], off offset:960
	global_load_dwordx4 v[152:155], v[6:7], off offset:896
	global_load_dwordx4 v[156:159], v[6:7], off offset:960
	global_load_dwordx4 v[160:163], v[8:9], off offset:896
	global_load_dwordx4 v[164:167], v[8:9], off offset:960
	global_load_dwordx4 v[168:171], v[10:11], off offset:896
	global_load_dwordx4 v[172:175], v[10:11], off offset:960
	s_waitcnt vmcnt(25)
	v_mfma_f32_16x16x32_bf16 v[28:31], v[228:231], v[176:179], v[28:31]
	v_mfma_f32_16x16x32_bf16 v[16:19], v[196:199], v[176:179], v[16:19]
	v_mfma_f32_16x16x32_bf16 v[20:23], v[204:207], v[176:179], v[20:23]
	v_mfma_f32_16x16x32_bf16 v[24:27], v[212:215], v[176:179], v[24:27]
	s_waitcnt vmcnt(24)
	v_mfma_f32_16x16x32_bf16 v[28:31], v[232:235], v[180:183], v[28:31]
	v_mfma_f32_16x16x32_bf16 v[32:35], v[196:199], v[188:191], v[32:35]
	v_mfma_f32_16x16x32_bf16 v[36:39], v[204:207], v[188:191], v[36:39]
	v_mfma_f32_16x16x32_bf16 v[40:43], v[212:215], v[188:191], v[40:43]
	v_mfma_f32_16x16x32_bf16 v[44:47], v[228:231], v[188:191], v[44:47]
	v_mfma_f32_16x16x32_bf16 v[16:19], v[200:203], v[180:183], v[16:19]
	v_mfma_f32_16x16x32_bf16 v[20:23], v[208:211], v[180:183], v[20:23]
	v_mfma_f32_16x16x32_bf16 v[24:27], v[224:227], v[180:183], v[24:27]
	v_mfma_f32_16x16x32_bf16 v[32:35], v[200:203], v[192:195], v[32:35]
	v_mfma_f32_16x16x32_bf16 v[36:39], v[208:211], v[192:195], v[36:39]
	v_mfma_f32_16x16x32_bf16 v[40:43], v[224:227], v[192:195], v[40:43]
	v_mfma_f32_16x16x32_bf16 v[44:47], v[232:235], v[192:195], v[44:47]
	global_load_dwordx4 v[176:179], v[0:1], off offset:1024
	global_load_dwordx4 v[180:183], v[0:1], off offset:1088
	global_load_dwordx4 v[188:191], v[2:3], off offset:1024
	global_load_dwordx4 v[192:195], v[2:3], off offset:1088
	global_load_dwordx4 v[196:199], v[4:5], off offset:1024
	global_load_dwordx4 v[200:203], v[4:5], off offset:1088
	global_load_dwordx4 v[204:207], v[6:7], off offset:1024
	global_load_dwordx4 v[208:211], v[6:7], off offset:1088
	global_load_dwordx4 v[212:215], v[8:9], off offset:1024
	global_load_dwordx4 v[224:227], v[8:9], off offset:1088
	global_load_dwordx4 v[228:231], v[10:11], off offset:1024
	global_load_dwordx4 v[232:235], v[10:11], off offset:1088
	s_waitcnt vmcnt(25)
	v_mfma_f32_16x16x32_bf16 v[28:31], v[120:123], v[48:51], v[28:31]
	v_mfma_f32_16x16x32_bf16 v[16:19], v[96:99], v[48:51], v[16:19]
	v_mfma_f32_16x16x32_bf16 v[20:23], v[104:107], v[48:51], v[20:23]
	v_mfma_f32_16x16x32_bf16 v[24:27], v[112:115], v[48:51], v[24:27]
	s_waitcnt vmcnt(24)
	v_mfma_f32_16x16x32_bf16 v[28:31], v[124:127], v[52:55], v[28:31]
	v_mfma_f32_16x16x32_bf16 v[32:35], v[96:99], v[56:59], v[32:35]
	v_mfma_f32_16x16x32_bf16 v[36:39], v[104:107], v[56:59], v[36:39]
	v_mfma_f32_16x16x32_bf16 v[40:43], v[112:115], v[56:59], v[40:43]
	v_mfma_f32_16x16x32_bf16 v[44:47], v[120:123], v[56:59], v[44:47]
	v_mfma_f32_16x16x32_bf16 v[16:19], v[100:103], v[52:55], v[16:19]
	v_mfma_f32_16x16x32_bf16 v[20:23], v[108:111], v[52:55], v[20:23]
	v_mfma_f32_16x16x32_bf16 v[24:27], v[116:119], v[52:55], v[24:27]
	v_mfma_f32_16x16x32_bf16 v[32:35], v[100:103], v[60:63], v[32:35]
	v_mfma_f32_16x16x32_bf16 v[36:39], v[108:111], v[60:63], v[36:39]
	v_mfma_f32_16x16x32_bf16 v[40:43], v[116:119], v[60:63], v[40:43]
	v_mfma_f32_16x16x32_bf16 v[44:47], v[124:127], v[60:63], v[44:47]
	global_load_dwordx4 v[48:51], v[0:1], off offset:1152
	global_load_dwordx4 v[52:55], v[0:1], off offset:1216
	global_load_dwordx4 v[56:59], v[2:3], off offset:1152
	global_load_dwordx4 v[60:63], v[2:3], off offset:1216
	global_load_dwordx4 v[96:99], v[4:5], off offset:1152
	global_load_dwordx4 v[100:103], v[4:5], off offset:1216
	global_load_dwordx4 v[104:107], v[6:7], off offset:1152
	global_load_dwordx4 v[108:111], v[6:7], off offset:1216
	global_load_dwordx4 v[112:115], v[8:9], off offset:1152
	global_load_dwordx4 v[116:119], v[8:9], off offset:1216
	global_load_dwordx4 v[120:123], v[10:11], off offset:1152
	global_load_dwordx4 v[124:127], v[10:11], off offset:1216
	s_waitcnt vmcnt(25)
	v_mfma_f32_16x16x32_bf16 v[28:31], v[168:171], v[128:131], v[28:31]
	v_mfma_f32_16x16x32_bf16 v[16:19], v[144:147], v[128:131], v[16:19]
	v_mfma_f32_16x16x32_bf16 v[20:23], v[152:155], v[128:131], v[20:23]
	v_mfma_f32_16x16x32_bf16 v[24:27], v[160:163], v[128:131], v[24:27]
	s_waitcnt vmcnt(24)
	v_mfma_f32_16x16x32_bf16 v[28:31], v[172:175], v[132:135], v[28:31]
	v_mfma_f32_16x16x32_bf16 v[32:35], v[144:147], v[136:139], v[32:35]
	v_mfma_f32_16x16x32_bf16 v[36:39], v[152:155], v[136:139], v[36:39]
	v_mfma_f32_16x16x32_bf16 v[40:43], v[160:163], v[136:139], v[40:43]
	v_mfma_f32_16x16x32_bf16 v[44:47], v[168:171], v[136:139], v[44:47]
	v_mfma_f32_16x16x32_bf16 v[16:19], v[148:151], v[132:135], v[16:19]
	v_mfma_f32_16x16x32_bf16 v[20:23], v[156:159], v[132:135], v[20:23]
	v_mfma_f32_16x16x32_bf16 v[24:27], v[164:167], v[132:135], v[24:27]
	v_mfma_f32_16x16x32_bf16 v[32:35], v[148:151], v[140:143], v[32:35]
	v_mfma_f32_16x16x32_bf16 v[36:39], v[156:159], v[140:143], v[36:39]
	v_mfma_f32_16x16x32_bf16 v[40:43], v[164:167], v[140:143], v[40:43]
	v_mfma_f32_16x16x32_bf16 v[44:47], v[172:175], v[140:143], v[44:47]
	global_load_dwordx4 v[128:131], v[0:1], off offset:1280
	global_load_dwordx4 v[132:135], v[0:1], off offset:1344
	global_load_dwordx4 v[136:139], v[2:3], off offset:1280
	global_load_dwordx4 v[140:143], v[2:3], off offset:1344
	global_load_dwordx4 v[144:147], v[4:5], off offset:1280
	global_load_dwordx4 v[148:151], v[4:5], off offset:1344
	global_load_dwordx4 v[152:155], v[6:7], off offset:1280
	global_load_dwordx4 v[156:159], v[6:7], off offset:1344
	global_load_dwordx4 v[160:163], v[8:9], off offset:1280
	global_load_dwordx4 v[164:167], v[8:9], off offset:1344
	global_load_dwordx4 v[168:171], v[10:11], off offset:1280
	global_load_dwordx4 v[172:175], v[10:11], off offset:1344
	s_waitcnt vmcnt(25)
	v_mfma_f32_16x16x32_bf16 v[28:31], v[228:231], v[176:179], v[28:31]
	v_mfma_f32_16x16x32_bf16 v[16:19], v[196:199], v[176:179], v[16:19]
	v_mfma_f32_16x16x32_bf16 v[20:23], v[204:207], v[176:179], v[20:23]
	v_mfma_f32_16x16x32_bf16 v[24:27], v[212:215], v[176:179], v[24:27]
	s_waitcnt vmcnt(24)
	v_mfma_f32_16x16x32_bf16 v[28:31], v[232:235], v[180:183], v[28:31]
	v_mfma_f32_16x16x32_bf16 v[32:35], v[196:199], v[188:191], v[32:35]
	v_mfma_f32_16x16x32_bf16 v[36:39], v[204:207], v[188:191], v[36:39]
	v_mfma_f32_16x16x32_bf16 v[40:43], v[212:215], v[188:191], v[40:43]
	v_mfma_f32_16x16x32_bf16 v[44:47], v[228:231], v[188:191], v[44:47]
	v_mfma_f32_16x16x32_bf16 v[16:19], v[200:203], v[180:183], v[16:19]
	v_mfma_f32_16x16x32_bf16 v[20:23], v[208:211], v[180:183], v[20:23]
	v_mfma_f32_16x16x32_bf16 v[24:27], v[224:227], v[180:183], v[24:27]
	v_mfma_f32_16x16x32_bf16 v[32:35], v[200:203], v[192:195], v[32:35]
	v_mfma_f32_16x16x32_bf16 v[36:39], v[208:211], v[192:195], v[36:39]
	v_mfma_f32_16x16x32_bf16 v[40:43], v[224:227], v[192:195], v[40:43]
	v_mfma_f32_16x16x32_bf16 v[44:47], v[232:235], v[192:195], v[44:47]
	s_waitcnt vmcnt(19)
	v_mfma_f32_16x16x32_bf16 v[16:19], v[96:99], v[48:51], v[16:19]
	s_waitcnt vmcnt(13)
	v_mfma_f32_16x16x32_bf16 v[28:31], v[120:123], v[48:51], v[28:31]
	v_mfma_f32_16x16x32_bf16 v[16:19], v[100:103], v[52:55], v[16:19]
	v_mfma_f32_16x16x32_bf16 v[20:23], v[104:107], v[48:51], v[20:23]
	v_mfma_f32_16x16x32_bf16 v[24:27], v[112:115], v[48:51], v[24:27]
	s_waitcnt vmcnt(12)
	v_mfma_f32_16x16x32_bf16 v[28:31], v[124:127], v[52:55], v[28:31]
	v_mfma_f32_16x16x32_bf16 v[32:35], v[96:99], v[56:59], v[32:35]
	v_mfma_f32_16x16x32_bf16 v[36:39], v[104:107], v[56:59], v[36:39]
	v_mfma_f32_16x16x32_bf16 v[40:43], v[112:115], v[56:59], v[40:43]
	v_mfma_f32_16x16x32_bf16 v[44:47], v[120:123], v[56:59], v[44:47]
	v_mfma_f32_16x16x32_bf16 v[20:23], v[108:111], v[52:55], v[20:23]
	v_mfma_f32_16x16x32_bf16 v[24:27], v[116:119], v[52:55], v[24:27]
	v_mfma_f32_16x16x32_bf16 v[32:35], v[100:103], v[60:63], v[32:35]
	v_mfma_f32_16x16x32_bf16 v[36:39], v[108:111], v[60:63], v[36:39]
	v_mfma_f32_16x16x32_bf16 v[40:43], v[116:119], v[60:63], v[40:43]
	v_mfma_f32_16x16x32_bf16 v[44:47], v[124:127], v[60:63], v[44:47]
	s_waitcnt vmcnt(7)
	v_mfma_f32_16x16x32_bf16 v[16:19], v[144:147], v[128:131], v[16:19]
	s_waitcnt vmcnt(6)
	v_mfma_f32_16x16x32_bf16 v[64:67], v[148:151], v[132:135], v[16:19]
	s_waitcnt vmcnt(5)
	v_mfma_f32_16x16x32_bf16 v[20:23], v[152:155], v[128:131], v[20:23]
	s_waitcnt vmcnt(4)
	v_mfma_f32_16x16x32_bf16 v[68:71], v[156:159], v[132:135], v[20:23]
	s_waitcnt vmcnt(3)
	v_mfma_f32_16x16x32_bf16 v[24:27], v[160:163], v[128:131], v[24:27]
	s_waitcnt vmcnt(2)
	v_mfma_f32_16x16x32_bf16 v[72:75], v[164:167], v[132:135], v[24:27]
	s_waitcnt vmcnt(1)
	v_mfma_f32_16x16x32_bf16 v[28:31], v[168:171], v[128:131], v[28:31]
	s_waitcnt vmcnt(0)
	v_mfma_f32_16x16x32_bf16 v[76:79], v[172:175], v[132:135], v[28:31]
	v_mfma_f32_16x16x32_bf16 v[36:39], v[152:155], v[136:139], v[36:39]
	v_mfma_f32_16x16x32_bf16 v[32:35], v[144:147], v[136:139], v[32:35]
	v_mfma_f32_16x16x32_bf16 v[4:7], v[156:159], v[140:143], v[36:39]
	v_mfma_f32_16x16x32_bf16 v[40:43], v[160:163], v[136:139], v[40:43]
	v_mfma_f32_16x16x32_bf16 v[44:47], v[168:171], v[136:139], v[44:47]
	v_mfma_f32_16x16x32_bf16 v[0:3], v[148:151], v[140:143], v[32:35]
	v_mfma_f32_16x16x32_bf16 v[8:11], v[164:167], v[140:143], v[40:43]
	v_mfma_f32_16x16x32_bf16 v[12:15], v[172:175], v[140:143], v[44:47]
	s_and_b64 vcc, exec, s[4:5]
	s_cbranch_vccnz .LBB0_1032
	v_add_u32_e32 v16, s18, v89
	ds_write_b128 v16, v[64:67]
	ds_write_b128 v16, v[68:71] offset:16
	ds_write_b128 v16, v[72:75] offset:32
	ds_write_b128 v16, v[76:79] offset:48
	ds_write_b128 v16, v[0:3] offset:64
	ds_write_b128 v16, v[4:7] offset:80
	ds_write_b128 v16, v[8:11] offset:96
	ds_write_b128 v16, v[12:15] offset:112
